# P0 weight conversions (w_down x2, branch_a/b, w_out, ffn2 gate/up) moved into idle GEMM tails of WGs 128-255; rsq epilogues
# speedup vs baseline: 1.0263x; 1.0255x over previous
; #define LAS __attribute__((address_space(3)))
; __device__ __forceinline__ void tr_load(const float* W, int N, int item, int lane, float (&wv)[32]) {
;     const int nblk = N / 32, kb = item / nblk, nb = item % nblk, k0 = 64 * kb, n0 = 32 * nb;
; #pragma unroll
;     for (int i = 0; i < 32; ++i) { const int kk = 2 * i + (lane >> 5); wv[i] = __builtin_nontemporal_load(W + (size_t)(k0 + kk) * N + n0 + (lane & 31)); }
; template <int MAP, bool HASG = false, bool PERMW = false>
; __device__ __forceinline__ void transpose_mat(const float* W, int K, int N, bf16_t* WT, LAS float* scr, int gw, int ngw, int lane, const float* gk = nullptr) {
;     const int nitems = (K / 64) * (N / 32);
;     int it = gw;
;     if (it >= nitems) return;
;     float wv[32];
;     tr_load(W, N, it, lane, wv);
.LBB0_70:
	s_andn2_b64 vcc, exec, s[4:5]
	s_branch .LBB0_83
	s_add_u32 s12, s7, 0x8a00000
	v_readlane_b32 s56, v254, 0
	s_addc_u32 s13, s25, 0
	s_lshl_b64 s[0:1], s[0:1], 2
	v_readlane_b32 s60, v254, 4
	v_readlane_b32 s61, v254, 5
	s_add_u32 s14, s60, s0
	v_readlane_b32 s62, v254, 6
	s_addc_u32 s15, s61, s1
	s_lshl_b64 s[0:1], s[90:91], 2
	v_readlane_b32 s63, v254, 7
	s_add_u32 s16, s62, s0
	s_addc_u32 s17, s63, s1
	s_lshr_b32 s4, s27, 31
	s_ashr_i32 s5, s27, 5
	s_add_i32 s5, s5, s4
	s_mul_i32 s4, s5, 0xb0
	s_sub_i32 s4, s6, s4
	s_lshl_b32 s4, s4, 5
	v_lshl_or_b32 v34, s5, 6, v134
	s_ashr_i32 s5, s4, 31
	s_lshl_b64 s[4:5], s[4:5], 2
	s_add_u32 s18, s16, s4
	s_addc_u32 s19, s17, s5
	v_mov_b32_e32 v47, v193
	v_lshl_add_u64 v[32:33], s[18:19], 0, v[46:47]
	s_waitcnt vmcnt(0)
	v_mad_i64_i32 v[0:1], s[18:19], v34, s55, v[32:33]
	global_load_dword v0, v[0:1], off nt
	v_or_b32_e32 v1, 2, v34
	s_waitcnt vmcnt(33)
	v_mad_i64_i32 v[2:3], s[18:19], v1, s55, v[32:33]
	v_mad_i64_i32 v[52:53], s[18:19], v1, s55, 0
	global_load_dword v1, v[2:3], off nt
	v_or_b32_e32 v2, 4, v34
	v_mad_i64_i32 v[54:55], s[18:19], v2, s55, 0
	v_mad_i64_i32 v[2:3], s[18:19], v2, s55, v[32:33]
	global_load_dword v2, v[2:3], off nt
	v_or_b32_e32 v3, 6, v34
	s_waitcnt vmcnt(33)
	v_mad_i64_i32 v[4:5], s[18:19], v3, s55, v[32:33]
	v_mad_i64_i32 v[56:57], s[18:19], v3, s55, 0
	global_load_dword v3, v[4:5], off nt
	v_or_b32_e32 v4, 8, v34
	v_mad_i64_i32 v[58:59], s[18:19], v4, s55, 0
	v_mad_i64_i32 v[4:5], s[18:19], v4, s55, v[32:33]
	global_load_dword v4, v[4:5], off nt
	v_or_b32_e32 v5, 10, v34
	s_waitcnt vmcnt(33)
	v_mad_i64_i32 v[6:7], s[18:19], v5, s55, v[32:33]
	v_mad_i64_i32 v[60:61], s[18:19], v5, s55, 0
	global_load_dword v5, v[6:7], off nt
	v_or_b32_e32 v6, 12, v34
	v_mad_i64_i32 v[62:63], s[18:19], v6, s55, 0
	v_mad_i64_i32 v[6:7], s[18:19], v6, s55, v[32:33]
	global_load_dword v6, v[6:7], off nt
	v_or_b32_e32 v7, 14, v34
	s_waitcnt vmcnt(33)
	v_mad_i64_i32 v[8:9], s[18:19], v7, s55, v[32:33]
	v_mad_i64_i32 v[64:65], s[18:19], v7, s55, 0
	global_load_dword v7, v[8:9], off nt
	v_or_b32_e32 v8, 16, v34
	v_mad_i64_i32 v[66:67], s[18:19], v8, s55, 0
	v_mad_i64_i32 v[8:9], s[18:19], v8, s55, v[32:33]
	global_load_dword v8, v[8:9], off nt
	v_or_b32_e32 v9, 18, v34
	s_waitcnt vmcnt(33)
	v_mad_i64_i32 v[10:11], s[18:19], v9, s55, v[32:33]
	v_mad_i64_i32 v[68:69], s[18:19], v9, s55, 0
	global_load_dword v9, v[10:11], off nt
	v_or_b32_e32 v10, 20, v34
	v_mad_i64_i32 v[70:71], s[18:19], v10, s55, 0
	v_mad_i64_i32 v[10:11], s[18:19], v10, s55, v[32:33]
	global_load_dword v10, v[10:11], off nt
	v_or_b32_e32 v11, 22, v34
	s_waitcnt vmcnt(33)
	v_mad_i64_i32 v[12:13], s[18:19], v11, s55, v[32:33]
	v_mad_i64_i32 v[72:73], s[18:19], v11, s55, 0
	global_load_dword v11, v[12:13], off nt
	v_or_b32_e32 v12, 24, v34
	v_mad_i64_i32 v[74:75], s[18:19], v12, s55, 0
	v_mad_i64_i32 v[12:13], s[18:19], v12, s55, v[32:33]
	global_load_dword v12, v[12:13], off nt
	v_or_b32_e32 v13, 26, v34
	s_waitcnt vmcnt(33)
	v_mad_i64_i32 v[14:15], s[18:19], v13, s55, v[32:33]
	v_mad_i64_i32 v[76:77], s[18:19], v13, s55, 0
	global_load_dword v13, v[14:15], off nt
	v_or_b32_e32 v14, 28, v34
	v_mad_i64_i32 v[78:79], s[18:19], v14, s55, 0
	v_mad_i64_i32 v[14:15], s[18:19], v14, s55, v[32:33]
	global_load_dword v14, v[14:15], off nt
	v_or_b32_e32 v15, 30, v34
	s_waitcnt vmcnt(33)
	v_mad_i64_i32 v[16:17], s[18:19], v15, s55, v[32:33]
	v_mad_i64_i32 v[80:81], s[18:19], v15, s55, 0
	global_load_dword v15, v[16:17], off nt
	v_or_b32_e32 v16, 32, v34
	v_mad_i64_i32 v[82:83], s[18:19], v16, s55, 0
	v_mad_i64_i32 v[16:17], s[18:19], v16, s55, v[32:33]
	global_load_dword v16, v[16:17], off nt
	v_or_b32_e32 v17, 34, v34
	s_waitcnt vmcnt(33)
; #define LAS __attribute__((address_space(3)))
; __device__ __forceinline__ unsigned pk2(float lo, float hi) { f32x2 f = {lo, hi}; bf16x2_t b = __builtin_convertvector(f, bf16x2_t); return __builtin_bit_cast(unsigned, b); }
; __device__ __forceinline__ void tr_load(const float* W, int N, int item, int lane, float (&wv)[32]) {
;     const int nblk = N / 32, kb = item / nblk, nb = item % nblk, k0 = 64 * kb, n0 = 32 * nb;
; #pragma unroll
;     for (int i = 0; i < 32; ++i) { const int kk = 2 * i + (lane >> 5); wv[i] = __builtin_nontemporal_load(W + (size_t)(k0 + kk) * N + n0 + (lane & 31)); }
; template <int MAP, bool HASG, bool PERMW>
; __device__ __forceinline__ void tr_store(int K, int N, bf16_t* WT, LAS float* scr, int item, int lane, const float* gk) {
;     const int nblk = N / 32, kb = item / nblk, nb = item % nblk, k0 = 64 * kb, n0 = 32 * nb;
;     asm volatile("s_waitcnt lgkmcnt(0)" ::: "memory");
;     const int c = lane & 7;
;     f32x4 g0 = {1.f, 1.f, 1.f, 1.f}, g1 = {1.f, 1.f, 1.f, 1.f};
;     if (HASG) { g0 = *(const f32x4*)(gk + k0 + 8 * c); g1 = *(const f32x4*)(gk + k0 + 8 * c + 4); }
; #pragma unroll
;     for (int j = 0; j < 4; ++j) { const int n = (lane >> 3) + 8 * j; const LAS float* s = scr + (8 * c) * 33 + n;
;         u32x4 o; o.x = pk2(s[0 * 33] * g0[0], s[1 * 33] * g0[1]); o.y = pk2(s[2 * 33] * g0[2], s[3 * 33] * g0[3]); o.z = pk2(s[4 * 33] * g1[0], s[5 * 33] * g1[1]); o.w = pk2(s[6 * 33] * g1[2], s[7 * 33] * g1[3]);
;         const int wr_ = rowmap<MAP>(n0 + n), slot_ = PERMW ? ((wr_ & ~31) + invperm32(wr_ & 31)) : wr_;
;         *(u32x4*)((char*)WT + tiled_off(slot_, k0 + 8 * c, K / 64)) = o; }
	v_mad_i64_i32 v[18:19], s[18:19], v17, s55, v[32:33]
	v_mad_i64_i32 v[84:85], s[18:19], v17, s55, 0
	global_load_dword v17, v[18:19], off nt
	v_or_b32_e32 v18, 36, v34
	v_mad_i64_i32 v[86:87], s[18:19], v18, s55, 0
	v_mad_i64_i32 v[18:19], s[18:19], v18, s55, v[32:33]
	global_load_dword v18, v[18:19], off nt
	v_or_b32_e32 v19, 38, v34
	s_waitcnt vmcnt(33)
	v_mad_i64_i32 v[20:21], s[18:19], v19, s55, v[32:33]
	v_mad_i64_i32 v[88:89], s[18:19], v19, s55, 0
	global_load_dword v19, v[20:21], off nt
	v_or_b32_e32 v20, 40, v34
	v_mad_i64_i32 v[90:91], s[18:19], v20, s55, 0
	v_mad_i64_i32 v[20:21], s[18:19], v20, s55, v[32:33]
	global_load_dword v20, v[20:21], off nt
	v_or_b32_e32 v21, 42, v34
	s_waitcnt vmcnt(33)
	v_mad_i64_i32 v[22:23], s[18:19], v21, s55, v[32:33]
	v_mad_i64_i32 v[92:93], s[18:19], v21, s55, 0
	global_load_dword v21, v[22:23], off nt
	v_or_b32_e32 v22, 44, v34
	v_mad_i64_i32 v[94:95], s[18:19], v22, s55, 0
	v_mad_i64_i32 v[22:23], s[18:19], v22, s55, v[32:33]
	global_load_dword v22, v[22:23], off nt
	v_or_b32_e32 v23, 46, v34
	s_waitcnt vmcnt(33)
	v_mad_i64_i32 v[24:25], s[18:19], v23, s55, v[32:33]
	v_mad_i64_i32 v[96:97], s[18:19], v23, s55, 0
	global_load_dword v23, v[24:25], off nt
	v_or_b32_e32 v24, 48, v34
	v_mad_i64_i32 v[98:99], s[18:19], v24, s55, 0
	v_mad_i64_i32 v[24:25], s[18:19], v24, s55, v[32:33]
	global_load_dword v24, v[24:25], off nt
	v_or_b32_e32 v25, 50, v34
	s_waitcnt vmcnt(33)
	v_mad_i64_i32 v[26:27], s[18:19], v25, s55, v[32:33]
	v_mad_i64_i32 v[100:101], s[18:19], v25, s55, 0
	global_load_dword v25, v[26:27], off nt
	v_or_b32_e32 v26, 52, v34
	v_mad_i64_i32 v[102:103], s[18:19], v26, s55, 0
	v_mad_i64_i32 v[26:27], s[18:19], v26, s55, v[32:33]
	global_load_dword v26, v[26:27], off nt
	v_or_b32_e32 v27, 54, v34
	s_waitcnt vmcnt(33)
	v_mad_i64_i32 v[28:29], s[18:19], v27, s55, v[32:33]
	v_mad_i64_i32 v[104:105], s[18:19], v27, s55, 0
	global_load_dword v27, v[28:29], off nt
	v_or_b32_e32 v28, 56, v34
	v_mad_i64_i32 v[106:107], s[18:19], v28, s55, 0
	v_mad_i64_i32 v[28:29], s[18:19], v28, s55, v[32:33]
	global_load_dword v28, v[28:29], off nt
	v_or_b32_e32 v29, 58, v34
	s_waitcnt vmcnt(33)
	v_mad_i64_i32 v[30:31], s[18:19], v29, s55, v[32:33]
	v_mad_i64_i32 v[108:109], s[18:19], v29, s55, 0
	global_load_dword v29, v[30:31], off nt
	v_or_b32_e32 v30, 60, v34
	v_mad_i64_i32 v[110:111], s[18:19], v30, s55, 0
	v_mad_i64_i32 v[30:31], s[18:19], v30, s55, v[32:33]
	global_load_dword v30, v[30:31], off nt
	v_or_b32_e32 v31, 62, v34
	v_mad_i64_i32 v[32:33], s[18:19], v31, s55, v[32:33]
	v_mad_i64_i32 v[112:113], s[18:19], v31, s55, 0
	global_load_dword v31, v[32:33], off nt
	v_lshlrev_b32_e32 v33, 3, v132
	v_mad_i64_i32 v[50:51], s[18:19], v34, s55, 0
	v_and_b32_e32 v34, 56, v33
	v_lshlrev_b32_e32 v192, 2, v34
	v_mul_u32_u24_e32 v34, 0x84, v34
	v_add3_u32 v49, s26, v34, v45
	v_lshlrev_b32_e32 v34, 4, v132
	v_add_u32_e32 v32, s26, v46
	v_lshl_add_u64 v[114:115], s[16:17], 0, v[46:47]
	v_and_b32_e32 v141, 48, v34
	s_lshl_b32 s17, s6, 5
	v_lshl_add_u64 v[46:47], s[14:15], 0, v[192:193]
	v_and_or_b32 v45, v33, s86, v141
	s_lshl_b32 s16, s8, 5
	v_add_u32_e32 v142, v32, v136
	s_mov_b32 s20, s17
	s_mov_b32 s21, s6
	v_readlane_b32 s57, v254, 1
	v_readlane_b32 s58, v254, 2
	v_readlane_b32 s59, v254, 3
	v_readlane_b32 s64, v254, 8
	v_readlane_b32 s65, v254, 9
	v_readlane_b32 s66, v254, 10
	v_readlane_b32 s67, v254, 11
	v_readlane_b32 s68, v254, 12
	v_readlane_b32 s69, v254, 13
	v_readlane_b32 s70, v254, 14
	v_readlane_b32 s71, v254, 15
	s_branch .LBB0_73

; #define LAS __attribute__((address_space(3)))
; __device__ __forceinline__ unsigned pk2(float lo, float hi) { f32x2 f = {lo, hi}; bf16x2_t b = __builtin_convertvector(f, bf16x2_t); return __builtin_bit_cast(unsigned, b); }
; __device__ __forceinline__ size_t tiled_off(int row, int col, int nkt) {
;     return ((size_t)(row >> 7) * nkt + (col >> 6)) * 16384 + (size_t)pg8::lds_byte(row & 127, col & 63);
; }
; template <int MAP, bool HASG, bool PERMW>
; __device__ __forceinline__ void tr_store(int K, int N, bf16_t* WT, LAS float* scr, int item, int lane, const float* gk) {
;     const int nblk = N / 32, kb = item / nblk, nb = item % nblk, k0 = 64 * kb, n0 = 32 * nb;
;     asm volatile("s_waitcnt lgkmcnt(0)" ::: "memory");
;     const int c = lane & 7;
;     f32x4 g0 = {1.f, 1.f, 1.f, 1.f}, g1 = {1.f, 1.f, 1.f, 1.f};
;     if (HASG) { g0 = *(const f32x4*)(gk + k0 + 8 * c); g1 = *(const f32x4*)(gk + k0 + 8 * c + 4); }
; #pragma unroll
;     for (int j = 0; j < 4; ++j) { const int n = (lane >> 3) + 8 * j; const LAS float* s = scr + (8 * c) * 33 + n;
;         u32x4 o; o.x = pk2(s[0 * 33] * g0[0], s[1 * 33] * g0[1]); o.y = pk2(s[2 * 33] * g0[2], s[3 * 33] * g0[3]); o.z = pk2(s[4 * 33] * g1[0], s[5 * 33] * g1[1]); o.w = pk2(s[6 * 33] * g1[2], s[7 * 33] * g1[3]);
;         const int wr_ = rowmap<MAP>(n0 + n), slot_ = PERMW ? ((wr_ & ~31) + invperm32(wr_ & 31)) : wr_;
;         *(u32x4*)((char*)WT + tiled_off(slot_, k0 + 8 * c, K / 64)) = o; }
.LBB0_158:
	s_cmpk_lt_u32 s2, 0x80
	s_cbranch_scc1 .Ltc1_done
	v_writelane_b32 v255, s4, 24
	v_writelane_b32 v255, s5, 25
	v_writelane_b32 v255, s6, 26
	v_writelane_b32 v255, s7, 27
	v_writelane_b32 v255, s8, 28
	v_writelane_b32 v255, s9, 29
	v_writelane_b32 v255, s10, 30
	v_writelane_b32 v255, s11, 31
	v_writelane_b32 v255, s12, 32
	v_writelane_b32 v255, s13, 33
	v_writelane_b32 v255, s14, 34
	v_writelane_b32 v255, s15, 35
	v_writelane_b32 v255, s16, 36
	v_writelane_b32 v255, s17, 37
	v_writelane_b32 v255, s18, 38
	v_writelane_b32 v255, s19, 39
	v_writelane_b32 v255, s20, 40
	v_writelane_b32 v255, s21, 41
	v_writelane_b32 v255, s22, 42
	v_writelane_b32 v255, s23, 43
	v_readfirstlane_b32 s8, v234
	s_nop 3
	s_lshr_b32 s8, s8, 6
	s_sub_u32 s18, s2, 0x80
	s_lshl_b32 s18, s18, 3
	s_add_u32 s18, s18, s8
	s_mul_i32 s10, s8, 0x2100
	v_and_b32_e32 v0, 63, v234
	v_and_b32_e32 v1, 31, v0
	v_lshrrev_b32_e32 v2, 5, v0
	v_lshlrev_b32_e32 v3, 13, v2
	v_lshl_add_u32 v3, v1, 2, v3
	v_mul_u32_u24_e32 v4, 33, v2
	v_add_u32_e32 v4, v4, v1
	v_lshl_add_u32 v4, v4, 2, s10
	v_and_b32_e32 v5, 7, v0
	v_lshrrev_b32_e32 v6, 3, v0
	v_mul_u32_u24_e32 v7, 0x108, v5
	v_add_u32_e32 v7, v7, v6
	v_lshl_add_u32 v7, v7, 2, s10
	v_lshrrev_b32_e32 v12, 2, v5
	v_lshlrev_b32_e32 v12, 10, v12
	v_and_b32_e32 v13, 3, v5
	v_lshl_add_u32 v12, v13, 4, v12
	v_lshl_add_u32 v8, v6, 6, v12
	v_xor_b32_e32 v9, 32, v8
	v_add_u32_e32 v9, 0x200, v9
	v_and_b32_e32 v13, 3, v6
	v_lshl_add_u32 v10, v13, 6, v12
	v_bfe_u32 v13, v6, 2, 1
	v_lshl_add_u32 v10, v13, 11, v10
	v_xor_b32_e32 v11, 32, v10
	v_lshlrev_b32_e32 v14, 5, v5
	v_mul_u32_u24_e32 v15, 0x5800, v2
	v_lshl_add_u32 v15, v1, 2, v15
	v_readlane_b32 s4, v255, 4
	v_readlane_b32 s5, v255, 5
	s_nop 3
	s_and_b32 s6, s60, 0x2c00000
	s_add_u32 s4, s4, s6
	s_addc_u32 s5, s5, 0
	s_add_u32 s6, s76, 0x2c00000
	s_addc_u32 s7, s77, 0
	s_mov_b32 s9, s18

; #define LAS __attribute__((address_space(3)))
; __device__ __forceinline__ void tr_load(const float* W, int N, int item, int lane, float (&wv)[32]) {
;     const int nblk = N / 32, kb = item / nblk, nb = item % nblk, k0 = 64 * kb, n0 = 32 * nb;
; #pragma unroll
;     for (int i = 0; i < 32; ++i) { const int kk = 2 * i + (lane >> 5); wv[i] = __builtin_nontemporal_load(W + (size_t)(k0 + kk) * N + n0 + (lane & 31)); }
; template <int MAP, bool HASG, bool PERMW>
; __device__ __forceinline__ void tr_store(int K, int N, bf16_t* WT, LAS float* scr, int item, int lane, const float* gk) {
;     const int nblk = N / 32, kb = item / nblk, nb = item % nblk, k0 = 64 * kb, n0 = 32 * nb;
;     asm volatile("s_waitcnt lgkmcnt(0)" ::: "memory");
;     const int c = lane & 7;
;     f32x4 g0 = {1.f, 1.f, 1.f, 1.f}, g1 = {1.f, 1.f, 1.f, 1.f};
;     if (HASG) { g0 = *(const f32x4*)(gk + k0 + 8 * c); g1 = *(const f32x4*)(gk + k0 + 8 * c + 4); }
.Ltc1a_exit:
	v_readlane_b32 s4, v254, 6
	v_readlane_b32 s5, v254, 7
	v_readlane_b32 s20, v254, 4
	v_readlane_b32 s21, v254, 5
	s_nop 3
	s_and_b32 s6, s60, 0x2c00000
	s_add_u32 s4, s4, s6
	s_addc_u32 s5, s5, 0
	s_and_b32 s6, s60, 0x2000
	s_add_u32 s20, s20, s6
	s_addc_u32 s21, s21, 0
	s_add_u32 s6, s76, 0x8a00000
	s_addc_u32 s7, s77, 0
	s_mov_b32 s9, s18
.Ltc1b_loop:
	s_cmpk_ge_u32 s9, 0x1600
	s_cbranch_scc1 .Ltc1b_exit
	s_mul_hi_u32 s11, s9, 0x2e8ba2e9
	s_lshr_b32 s11, s11, 5
	s_mul_i32 s12, s11, 0xb0
	s_sub_u32 s12, s9, s12
	s_mul_i32 s13, s11, 0x160000
	s_lshl_b32 s14, s12, 7
	s_add_u32 s13, s13, s14
	s_add_u32 s14, s4, s13
	s_addc_u32 s15, s5, 0
	global_load_dword v16, v15, s[14:15] nt
	s_add_u32 s14, s14, 0xb000
	s_addc_u32 s15, s15, 0
	global_load_dword v17, v15, s[14:15] nt
	s_add_u32 s14, s14, 0xb000
	s_addc_u32 s15, s15, 0
	global_load_dword v18, v15, s[14:15] nt
	s_add_u32 s14, s14, 0xb000
	s_addc_u32 s15, s15, 0
	global_load_dword v19, v15, s[14:15] nt
	s_add_u32 s14, s14, 0xb000
	s_addc_u32 s15, s15, 0
	global_load_dword v20, v15, s[14:15] nt
	s_add_u32 s14, s14, 0xb000
	s_addc_u32 s15, s15, 0
	global_load_dword v21, v15, s[14:15] nt
	s_add_u32 s14, s14, 0xb000
	s_addc_u32 s15, s15, 0
	global_load_dword v22, v15, s[14:15] nt
	s_add_u32 s14, s14, 0xb000
	s_addc_u32 s15, s15, 0
	global_load_dword v23, v15, s[14:15] nt
	s_add_u32 s14, s14, 0xb000
	s_addc_u32 s15, s15, 0
	global_load_dword v24, v15, s[14:15] nt
	s_add_u32 s14, s14, 0xb000
	s_addc_u32 s15, s15, 0
	global_load_dword v25, v15, s[14:15] nt
	s_add_u32 s14, s14, 0xb000
	s_addc_u32 s15, s15, 0
	global_load_dword v26, v15, s[14:15] nt
	s_add_u32 s14, s14, 0xb000
	s_addc_u32 s15, s15, 0
	global_load_dword v27, v15, s[14:15] nt
	s_add_u32 s14, s14, 0xb000
	s_addc_u32 s15, s15, 0
	global_load_dword v28, v15, s[14:15] nt
	s_add_u32 s14, s14, 0xb000
	s_addc_u32 s15, s15, 0
	global_load_dword v29, v15, s[14:15] nt
	s_add_u32 s14, s14, 0xb000
	s_addc_u32 s15, s15, 0
	global_load_dword v30, v15, s[14:15] nt
	s_add_u32 s14, s14, 0xb000
	s_addc_u32 s15, s15, 0
	global_load_dword v31, v15, s[14:15] nt
	s_add_u32 s14, s14, 0xb000
	s_addc_u32 s15, s15, 0
	global_load_dword v32, v15, s[14:15] nt
	s_add_u32 s14, s14, 0xb000
	s_addc_u32 s15, s15, 0
	global_load_dword v33, v15, s[14:15] nt
	s_add_u32 s14, s14, 0xb000
	s_addc_u32 s15, s15, 0
	global_load_dword v34, v15, s[14:15] nt
	s_add_u32 s14, s14, 0xb000
	s_addc_u32 s15, s15, 0
	global_load_dword v35, v15, s[14:15] nt
	s_add_u32 s14, s14, 0xb000
	s_addc_u32 s15, s15, 0
	global_load_dword v36, v15, s[14:15] nt
	s_add_u32 s14, s14, 0xb000
	s_addc_u32 s15, s15, 0
	global_load_dword v37, v15, s[14:15] nt
	s_add_u32 s14, s14, 0xb000
	s_addc_u32 s15, s15, 0
	global_load_dword v38, v15, s[14:15] nt
	s_add_u32 s14, s14, 0xb000
	s_addc_u32 s15, s15, 0
	global_load_dword v39, v15, s[14:15] nt
	s_add_u32 s14, s14, 0xb000
	s_addc_u32 s15, s15, 0
	global_load_dword v40, v15, s[14:15] nt
	s_add_u32 s14, s14, 0xb000
	s_addc_u32 s15, s15, 0
	global_load_dword v41, v15, s[14:15] nt
	s_add_u32 s14, s14, 0xb000
	s_addc_u32 s15, s15, 0
	global_load_dword v42, v15, s[14:15] nt
	s_add_u32 s14, s14, 0xb000
	s_addc_u32 s15, s15, 0
	global_load_dword v43, v15, s[14:15] nt
	s_add_u32 s14, s14, 0xb000
	s_addc_u32 s15, s15, 0
	global_load_dword v44, v15, s[14:15] nt
	s_add_u32 s14, s14, 0xb000
	s_addc_u32 s15, s15, 0
	global_load_dword v45, v15, s[14:15] nt
	s_add_u32 s14, s14, 0xb000
	s_addc_u32 s15, s15, 0
	global_load_dword v46, v15, s[14:15] nt
	s_add_u32 s14, s14, 0xb000
	s_addc_u32 s15, s15, 0
	global_load_dword v47, v15, s[14:15] nt
	s_lshl_b32 s22, s11, 8
	s_add_u32 s22, s20, s22
	s_addc_u32 s23, s21, 0
	global_load_dwordx4 v[80:83], v14, s[22:23]
	global_load_dwordx4 v[84:87], v14, s[22:23] offset:16
	s_lshr_b32 s16, s12, 2
	s_lshl_b32 s16, s16, 1
	s_lshl_b32 s16, s16, 5
	s_add_u32 s16, s16, s11
	s_lshl_b32 s16, s16, 14
	s_and_b32 s17, s12, 3
	s_lshl_b32 s17, s17, 12
	s_add_u32 s16, s16, s17
	s_add_u32 s16, s6, s16
	s_addc_u32 s17, s7, 0
	s_waitcnt vmcnt(0)
; #define LAS __attribute__((address_space(3)))
; __device__ __forceinline__ unsigned pk2(float lo, float hi) { f32x2 f = {lo, hi}; bf16x2_t b = __builtin_convertvector(f, bf16x2_t); return __builtin_bit_cast(unsigned, b); }
; template <int MAP, bool HASG, bool PERMW>
; __device__ __forceinline__ void tr_store(int K, int N, bf16_t* WT, LAS float* scr, int item, int lane, const float* gk) {
;     const int nblk = N / 32, kb = item / nblk, nb = item % nblk, k0 = 64 * kb, n0 = 32 * nb;
;     asm volatile("s_waitcnt lgkmcnt(0)" ::: "memory");
;     const int c = lane & 7;
;     f32x4 g0 = {1.f, 1.f, 1.f, 1.f}, g1 = {1.f, 1.f, 1.f, 1.f};
;     if (HASG) { g0 = *(const f32x4*)(gk + k0 + 8 * c); g1 = *(const f32x4*)(gk + k0 + 8 * c + 4); }
; #pragma unroll
;     for (int j = 0; j < 4; ++j) { const int n = (lane >> 3) + 8 * j; const LAS float* s = scr + (8 * c) * 33 + n;
;         u32x4 o; o.x = pk2(s[0 * 33] * g0[0], s[1 * 33] * g0[1]); o.y = pk2(s[2 * 33] * g0[2], s[3 * 33] * g0[3]); o.z = pk2(s[4 * 33] * g1[0], s[5 * 33] * g1[1]); o.w = pk2(s[6 * 33] * g1[2], s[7 * 33] * g1[3]);
;         const int wr_ = rowmap<MAP>(n0 + n), slot_ = PERMW ? ((wr_ & ~31) + invperm32(wr_ & 31)) : wr_;
;         *(u32x4*)((char*)WT + tiled_off(slot_, k0 + 8 * c, K / 64)) = o; }
;     asm volatile("s_waitcnt lgkmcnt(0)" ::: "memory");
	ds_write_b32 v4, v16
	ds_write_b32 v4, v17 offset:264
	ds_write_b32 v4, v18 offset:528
	ds_write_b32 v4, v19 offset:792
	ds_write_b32 v4, v20 offset:1056
	ds_write_b32 v4, v21 offset:1320
	ds_write_b32 v4, v22 offset:1584
	ds_write_b32 v4, v23 offset:1848
	ds_write_b32 v4, v24 offset:2112
	ds_write_b32 v4, v25 offset:2376
	ds_write_b32 v4, v26 offset:2640
	ds_write_b32 v4, v27 offset:2904
	ds_write_b32 v4, v28 offset:3168
	ds_write_b32 v4, v29 offset:3432
	ds_write_b32 v4, v30 offset:3696
	ds_write_b32 v4, v31 offset:3960
	ds_write_b32 v4, v32 offset:4224
	ds_write_b32 v4, v33 offset:4488
	ds_write_b32 v4, v34 offset:4752
	ds_write_b32 v4, v35 offset:5016
	ds_write_b32 v4, v36 offset:5280
	ds_write_b32 v4, v37 offset:5544
	ds_write_b32 v4, v38 offset:5808
	ds_write_b32 v4, v39 offset:6072
	ds_write_b32 v4, v40 offset:6336
	ds_write_b32 v4, v41 offset:6600
	ds_write_b32 v4, v42 offset:6864
	ds_write_b32 v4, v43 offset:7128
	ds_write_b32 v4, v44 offset:7392
	ds_write_b32 v4, v45 offset:7656
	ds_write_b32 v4, v46 offset:7920
	ds_write_b32 v4, v47 offset:8184
	s_waitcnt lgkmcnt(0)
	ds_read_b32 v48, v7
	ds_read_b32 v49, v7 offset:132
	ds_read_b32 v50, v7 offset:264
	ds_read_b32 v51, v7 offset:396
	ds_read_b32 v52, v7 offset:528
	ds_read_b32 v53, v7 offset:660
	ds_read_b32 v54, v7 offset:792
	ds_read_b32 v55, v7 offset:924
	ds_read_b32 v56, v7 offset:32
	ds_read_b32 v57, v7 offset:164
	ds_read_b32 v58, v7 offset:296
	ds_read_b32 v59, v7 offset:428
	ds_read_b32 v60, v7 offset:560
	ds_read_b32 v61, v7 offset:692
	ds_read_b32 v62, v7 offset:824
	ds_read_b32 v63, v7 offset:956
	ds_read_b32 v64, v7 offset:64
	ds_read_b32 v65, v7 offset:196
	ds_read_b32 v66, v7 offset:328
	ds_read_b32 v67, v7 offset:460
	ds_read_b32 v68, v7 offset:592
	ds_read_b32 v69, v7 offset:724
	ds_read_b32 v70, v7 offset:856
	ds_read_b32 v71, v7 offset:988
	ds_read_b32 v72, v7 offset:96
	ds_read_b32 v73, v7 offset:228
	ds_read_b32 v74, v7 offset:360
	ds_read_b32 v75, v7 offset:492
	ds_read_b32 v76, v7 offset:624
	ds_read_b32 v77, v7 offset:756
	ds_read_b32 v78, v7 offset:888
	ds_read_b32 v79, v7 offset:1020
	s_waitcnt lgkmcnt(0)
	v_mul_f32_e32 v48, v48, v80
	v_mul_f32_e32 v49, v49, v81
	v_mul_f32_e32 v50, v50, v82
	v_mul_f32_e32 v51, v51, v83
	v_mul_f32_e32 v52, v52, v84
	v_mul_f32_e32 v53, v53, v85
	v_mul_f32_e32 v54, v54, v86
	v_mul_f32_e32 v55, v55, v87
	v_cvt_pk_bf16_f32 v48, v48, v49
	v_cvt_pk_bf16_f32 v49, v50, v51
	v_cvt_pk_bf16_f32 v50, v52, v53
	v_cvt_pk_bf16_f32 v51, v54, v55
	global_store_dwordx4 v10, v[48:51], s[16:17]
	v_mul_f32_e32 v56, v56, v80
	v_mul_f32_e32 v57, v57, v81
	v_mul_f32_e32 v58, v58, v82
	v_mul_f32_e32 v59, v59, v83
	v_mul_f32_e32 v60, v60, v84
	v_mul_f32_e32 v61, v61, v85
	v_mul_f32_e32 v62, v62, v86
	v_mul_f32_e32 v63, v63, v87
	v_cvt_pk_bf16_f32 v56, v56, v57
	v_cvt_pk_bf16_f32 v57, v58, v59
	v_cvt_pk_bf16_f32 v58, v60, v61
	v_cvt_pk_bf16_f32 v59, v62, v63
	global_store_dwordx4 v10, v[56:59], s[16:17] offset:256
	v_mul_f32_e32 v64, v64, v80
	v_mul_f32_e32 v65, v65, v81
	v_mul_f32_e32 v66, v66, v82
	v_mul_f32_e32 v67, v67, v83
	v_mul_f32_e32 v68, v68, v84
	v_mul_f32_e32 v69, v69, v85
	v_mul_f32_e32 v70, v70, v86
	v_mul_f32_e32 v71, v71, v87
	v_cvt_pk_bf16_f32 v64, v64, v65
	v_cvt_pk_bf16_f32 v65, v66, v67
	v_cvt_pk_bf16_f32 v66, v68, v69
	v_cvt_pk_bf16_f32 v67, v70, v71
	global_store_dwordx4 v11, v[64:67], s[16:17] offset:512
	v_mul_f32_e32 v72, v72, v80
	v_mul_f32_e32 v73, v73, v81
	v_mul_f32_e32 v74, v74, v82
	v_mul_f32_e32 v75, v75, v83
	v_mul_f32_e32 v76, v76, v84
	v_mul_f32_e32 v77, v77, v85
	v_mul_f32_e32 v78, v78, v86
	v_mul_f32_e32 v79, v79, v87
	v_cvt_pk_bf16_f32 v72, v72, v73
	v_cvt_pk_bf16_f32 v73, v74, v75
	v_cvt_pk_bf16_f32 v74, v76, v77
	v_cvt_pk_bf16_f32 v75, v78, v79
	global_store_dwordx4 v11, v[72:75], s[16:17] offset:768
	s_add_u32 s9, s9, 0x400
	s_branch .Ltc1b_loop
.Ltc1b_exit:
	v_readlane_b32 s4, v255, 24
	v_readlane_b32 s5, v255, 25
	v_readlane_b32 s6, v255, 26
	v_readlane_b32 s7, v255, 27
	v_readlane_b32 s8, v255, 28
	v_readlane_b32 s9, v255, 29
	v_readlane_b32 s10, v255, 30
	v_readlane_b32 s11, v255, 31
	v_readlane_b32 s12, v255, 32
	v_readlane_b32 s13, v255, 33
	v_readlane_b32 s14, v255, 34
	v_readlane_b32 s15, v255, 35
	v_readlane_b32 s16, v255, 36
	v_readlane_b32 s17, v255, 37
	v_readlane_b32 s18, v255, 38
	v_readlane_b32 s19, v255, 39
	v_readlane_b32 s20, v255, 40
	v_readlane_b32 s21, v255, 41
	v_readlane_b32 s22, v255, 42
	v_readlane_b32 s23, v255, 43
	s_nop 3

; #define LAS __attribute__((address_space(3)))
; __device__ __forceinline__ unsigned pk2(float lo, float hi) { f32x2 f = {lo, hi}; bf16x2_t b = __builtin_convertvector(f, bf16x2_t); return __builtin_bit_cast(unsigned, b); }
; __device__ __forceinline__ size_t tiled_off(int row, int col, int nkt) {
;     return ((size_t)(row >> 7) * nkt + (col >> 6)) * 16384 + (size_t)pg8::lds_byte(row & 127, col & 63);
; }
; template <int MAP, bool HASG, bool PERMW>
; __device__ __forceinline__ void tr_store(int K, int N, bf16_t* WT, LAS float* scr, int item, int lane, const float* gk) {
;     const int nblk = N / 32, kb = item / nblk, nb = item % nblk, k0 = 64 * kb, n0 = 32 * nb;
;     asm volatile("s_waitcnt lgkmcnt(0)" ::: "memory");
;     const int c = lane & 7;
;     f32x4 g0 = {1.f, 1.f, 1.f, 1.f}, g1 = {1.f, 1.f, 1.f, 1.f};
;     if (HASG) { g0 = *(const f32x4*)(gk + k0 + 8 * c); g1 = *(const f32x4*)(gk + k0 + 8 * c + 4); }
; #pragma unroll
;     for (int j = 0; j < 4; ++j) { const int n = (lane >> 3) + 8 * j; const LAS float* s = scr + (8 * c) * 33 + n;
;         u32x4 o; o.x = pk2(s[0 * 33] * g0[0], s[1 * 33] * g0[1]); o.y = pk2(s[2 * 33] * g0[2], s[3 * 33] * g0[3]); o.z = pk2(s[4 * 33] * g1[0], s[5 * 33] * g1[1]); o.w = pk2(s[6 * 33] * g1[2], s[7 * 33] * g1[3]);
;         const int wr_ = rowmap<MAP>(n0 + n), slot_ = PERMW ? ((wr_ & ~31) + invperm32(wr_ & 31)) : wr_;
;         *(u32x4*)((char*)WT + tiled_off(slot_, k0 + 8 * c, K / 64)) = o; }
.LBB0_378:
	s_cmpk_lt_u32 s2, 0x80
	s_cbranch_scc1 .Ltc3_done
	v_writelane_b32 v255, s4, 24
	v_writelane_b32 v255, s5, 25
	v_writelane_b32 v255, s6, 26
	v_writelane_b32 v255, s7, 27
	v_writelane_b32 v255, s8, 28
	v_writelane_b32 v255, s9, 29
	v_writelane_b32 v255, s10, 30
	v_writelane_b32 v255, s11, 31
	v_writelane_b32 v255, s12, 32
	v_writelane_b32 v255, s13, 33
	v_writelane_b32 v255, s14, 34
	v_writelane_b32 v255, s15, 35
	v_writelane_b32 v255, s16, 36
	v_writelane_b32 v255, s17, 37
	v_writelane_b32 v255, s18, 38
	v_writelane_b32 v255, s19, 39
	v_writelane_b32 v255, s20, 40
	v_writelane_b32 v255, s21, 41
	v_writelane_b32 v255, s22, 42
	v_writelane_b32 v255, s23, 43
	v_readfirstlane_b32 s8, v234
	s_nop 3
	s_lshr_b32 s8, s8, 6
	s_sub_u32 s18, s2, 0x80
	s_lshl_b32 s18, s18, 3
	s_add_u32 s18, s18, s8
	s_mul_i32 s10, s8, 0x2100
	v_and_b32_e32 v0, 63, v234
	v_and_b32_e32 v1, 31, v0
	v_lshrrev_b32_e32 v2, 5, v0
	v_lshlrev_b32_e32 v3, 13, v2
	v_lshl_add_u32 v3, v1, 2, v3
	v_mul_u32_u24_e32 v4, 33, v2
	v_add_u32_e32 v4, v4, v1
	v_lshl_add_u32 v4, v4, 2, s10
	v_and_b32_e32 v5, 7, v0
	v_lshrrev_b32_e32 v6, 3, v0
	v_mul_u32_u24_e32 v7, 0x108, v5
	v_add_u32_e32 v7, v7, v6
	v_lshl_add_u32 v7, v7, 2, s10
	v_lshrrev_b32_e32 v12, 2, v5
	v_lshlrev_b32_e32 v12, 10, v12
	v_and_b32_e32 v13, 3, v5
	v_lshl_add_u32 v12, v13, 4, v12
	v_lshl_add_u32 v8, v6, 6, v12
	v_xor_b32_e32 v9, 32, v8
	v_add_u32_e32 v9, 0x200, v9
	v_and_b32_e32 v13, 3, v6
	v_lshl_add_u32 v10, v13, 6, v12
	v_bfe_u32 v13, v6, 2, 1
	v_lshl_add_u32 v10, v13, 11, v10
	v_xor_b32_e32 v11, 32, v10
	v_lshlrev_b32_e32 v14, 5, v5
	v_mul_u32_u24_e32 v15, 0x5800, v2
	v_lshl_add_u32 v15, v1, 2, v15
	v_readlane_b32 s4, v255, 10
	v_readlane_b32 s5, v255, 11
	s_nop 3
	s_and_b32 s6, s60, 0x800000
	s_add_u32 s4, s4, s6
	s_addc_u32 s5, s5, 0
	s_add_u32 s6, s76, 0x7600000
	s_addc_u32 s7, s77, 0
	s_mov_b32 s9, s18

; #define LAS __attribute__((address_space(3)))
; __device__ __forceinline__ void tr_load(const float* W, int N, int item, int lane, float (&wv)[32]) {
;     const int nblk = N / 32, kb = item / nblk, nb = item % nblk, k0 = 64 * kb, n0 = 32 * nb;
; #pragma unroll
;     for (int i = 0; i < 32; ++i) { const int kk = 2 * i + (lane >> 5); wv[i] = __builtin_nontemporal_load(W + (size_t)(k0 + kk) * N + n0 + (lane & 31)); }
; template <int MAP, bool HASG, bool PERMW>
; __device__ __forceinline__ void tr_store(int K, int N, bf16_t* WT, LAS float* scr, int item, int lane, const float* gk) {
;     const int nblk = N / 32, kb = item / nblk, nb = item % nblk, k0 = 64 * kb, n0 = 32 * nb;
;     asm volatile("s_waitcnt lgkmcnt(0)" ::: "memory");
;     const int c = lane & 7;
;     f32x4 g0 = {1.f, 1.f, 1.f, 1.f}, g1 = {1.f, 1.f, 1.f, 1.f};
;     if (HASG) { g0 = *(const f32x4*)(gk + k0 + 8 * c); g1 = *(const f32x4*)(gk + k0 + 8 * c + 4); }
.Ltc3c_exit:
	v_readlane_b32 s4, v254, 8
	v_readlane_b32 s5, v254, 9
	v_readlane_b32 s20, v254, 4
	v_readlane_b32 s21, v254, 5
	s_nop 3
	s_and_b32 s6, s60, 0x2c00000
	s_add_u32 s4, s4, s6
	s_addc_u32 s5, s5, 0
	s_and_b32 s6, s60, 0x2000
	s_add_u32 s20, s20, s6
	s_addc_u32 s21, s21, 0
	s_add_u32 s6, s76, 0x8a00000
	s_addc_u32 s7, s77, 0
	s_mov_b32 s9, s18
.Ltc3d_loop:
	s_cmpk_ge_u32 s9, 0x1600
	s_cbranch_scc1 .Ltc3d_exit
	s_mul_hi_u32 s11, s9, 0x2e8ba2e9
	s_lshr_b32 s11, s11, 5
	s_mul_i32 s12, s11, 0xb0
	s_sub_u32 s12, s9, s12
	s_mul_i32 s13, s11, 0x160000
	s_lshl_b32 s14, s12, 7
	s_add_u32 s13, s13, s14
	s_add_u32 s14, s4, s13
	s_addc_u32 s15, s5, 0
	global_load_dword v16, v15, s[14:15] nt
	s_add_u32 s14, s14, 0xb000
	s_addc_u32 s15, s15, 0
	global_load_dword v17, v15, s[14:15] nt
	s_add_u32 s14, s14, 0xb000
	s_addc_u32 s15, s15, 0
	global_load_dword v18, v15, s[14:15] nt
	s_add_u32 s14, s14, 0xb000
	s_addc_u32 s15, s15, 0
	global_load_dword v19, v15, s[14:15] nt
	s_add_u32 s14, s14, 0xb000
	s_addc_u32 s15, s15, 0
	global_load_dword v20, v15, s[14:15] nt
	s_add_u32 s14, s14, 0xb000
	s_addc_u32 s15, s15, 0
	global_load_dword v21, v15, s[14:15] nt
	s_add_u32 s14, s14, 0xb000
	s_addc_u32 s15, s15, 0
	global_load_dword v22, v15, s[14:15] nt
	s_add_u32 s14, s14, 0xb000
	s_addc_u32 s15, s15, 0
	global_load_dword v23, v15, s[14:15] nt
	s_add_u32 s14, s14, 0xb000
	s_addc_u32 s15, s15, 0
	global_load_dword v24, v15, s[14:15] nt
	s_add_u32 s14, s14, 0xb000
	s_addc_u32 s15, s15, 0
	global_load_dword v25, v15, s[14:15] nt
	s_add_u32 s14, s14, 0xb000
	s_addc_u32 s15, s15, 0
	global_load_dword v26, v15, s[14:15] nt
	s_add_u32 s14, s14, 0xb000
	s_addc_u32 s15, s15, 0
	global_load_dword v27, v15, s[14:15] nt
	s_add_u32 s14, s14, 0xb000
	s_addc_u32 s15, s15, 0
	global_load_dword v28, v15, s[14:15] nt
	s_add_u32 s14, s14, 0xb000
	s_addc_u32 s15, s15, 0
	global_load_dword v29, v15, s[14:15] nt
	s_add_u32 s14, s14, 0xb000
	s_addc_u32 s15, s15, 0
	global_load_dword v30, v15, s[14:15] nt
	s_add_u32 s14, s14, 0xb000
	s_addc_u32 s15, s15, 0
	global_load_dword v31, v15, s[14:15] nt
	s_add_u32 s14, s14, 0xb000
	s_addc_u32 s15, s15, 0
	global_load_dword v32, v15, s[14:15] nt
	s_add_u32 s14, s14, 0xb000
	s_addc_u32 s15, s15, 0
	global_load_dword v33, v15, s[14:15] nt
	s_add_u32 s14, s14, 0xb000
	s_addc_u32 s15, s15, 0
	global_load_dword v34, v15, s[14:15] nt
	s_add_u32 s14, s14, 0xb000
	s_addc_u32 s15, s15, 0
	global_load_dword v35, v15, s[14:15] nt
	s_add_u32 s14, s14, 0xb000
	s_addc_u32 s15, s15, 0
	global_load_dword v36, v15, s[14:15] nt
	s_add_u32 s14, s14, 0xb000
	s_addc_u32 s15, s15, 0
	global_load_dword v37, v15, s[14:15] nt
	s_add_u32 s14, s14, 0xb000
	s_addc_u32 s15, s15, 0
	global_load_dword v38, v15, s[14:15] nt
	s_add_u32 s14, s14, 0xb000
	s_addc_u32 s15, s15, 0
	global_load_dword v39, v15, s[14:15] nt
	s_add_u32 s14, s14, 0xb000
	s_addc_u32 s15, s15, 0
	global_load_dword v40, v15, s[14:15] nt
	s_add_u32 s14, s14, 0xb000
	s_addc_u32 s15, s15, 0
	global_load_dword v41, v15, s[14:15] nt
	s_add_u32 s14, s14, 0xb000
	s_addc_u32 s15, s15, 0
	global_load_dword v42, v15, s[14:15] nt
	s_add_u32 s14, s14, 0xb000
	s_addc_u32 s15, s15, 0
	global_load_dword v43, v15, s[14:15] nt
	s_add_u32 s14, s14, 0xb000
	s_addc_u32 s15, s15, 0
	global_load_dword v44, v15, s[14:15] nt
	s_add_u32 s14, s14, 0xb000
	s_addc_u32 s15, s15, 0
	global_load_dword v45, v15, s[14:15] nt
	s_add_u32 s14, s14, 0xb000
	s_addc_u32 s15, s15, 0
	global_load_dword v46, v15, s[14:15] nt
	s_add_u32 s14, s14, 0xb000
	s_addc_u32 s15, s15, 0
	global_load_dword v47, v15, s[14:15] nt
	s_lshl_b32 s22, s11, 8
	s_add_u32 s22, s20, s22
	s_addc_u32 s23, s21, 0
	global_load_dwordx4 v[80:83], v14, s[22:23]
	global_load_dwordx4 v[84:87], v14, s[22:23] offset:16
	s_lshr_b32 s16, s12, 2
	s_lshl_b32 s16, s16, 1
	s_add_u32 s16, s16, 1
	s_lshl_b32 s16, s16, 5
	s_add_u32 s16, s16, s11
	s_lshl_b32 s16, s16, 14
	s_and_b32 s17, s12, 3
	s_lshl_b32 s17, s17, 12
	s_add_u32 s16, s16, s17
	s_add_u32 s16, s6, s16
	s_addc_u32 s17, s7, 0
	s_waitcnt vmcnt(0)
; #define LAS __attribute__((address_space(3)))
; __device__ __forceinline__ unsigned pk2(float lo, float hi) { f32x2 f = {lo, hi}; bf16x2_t b = __builtin_convertvector(f, bf16x2_t); return __builtin_bit_cast(unsigned, b); }
; template <int MAP, bool HASG, bool PERMW>
; __device__ __forceinline__ void tr_store(int K, int N, bf16_t* WT, LAS float* scr, int item, int lane, const float* gk) {
;     const int nblk = N / 32, kb = item / nblk, nb = item % nblk, k0 = 64 * kb, n0 = 32 * nb;
;     asm volatile("s_waitcnt lgkmcnt(0)" ::: "memory");
;     const int c = lane & 7;
;     f32x4 g0 = {1.f, 1.f, 1.f, 1.f}, g1 = {1.f, 1.f, 1.f, 1.f};
;     if (HASG) { g0 = *(const f32x4*)(gk + k0 + 8 * c); g1 = *(const f32x4*)(gk + k0 + 8 * c + 4); }
; #pragma unroll
;     for (int j = 0; j < 4; ++j) { const int n = (lane >> 3) + 8 * j; const LAS float* s = scr + (8 * c) * 33 + n;
;         u32x4 o; o.x = pk2(s[0 * 33] * g0[0], s[1 * 33] * g0[1]); o.y = pk2(s[2 * 33] * g0[2], s[3 * 33] * g0[3]); o.z = pk2(s[4 * 33] * g1[0], s[5 * 33] * g1[1]); o.w = pk2(s[6 * 33] * g1[2], s[7 * 33] * g1[3]);
;         const int wr_ = rowmap<MAP>(n0 + n), slot_ = PERMW ? ((wr_ & ~31) + invperm32(wr_ & 31)) : wr_;
;         *(u32x4*)((char*)WT + tiled_off(slot_, k0 + 8 * c, K / 64)) = o; }
;     asm volatile("s_waitcnt lgkmcnt(0)" ::: "memory");
	ds_write_b32 v4, v16
	ds_write_b32 v4, v17 offset:264
	ds_write_b32 v4, v18 offset:528
	ds_write_b32 v4, v19 offset:792
	ds_write_b32 v4, v20 offset:1056
	ds_write_b32 v4, v21 offset:1320
	ds_write_b32 v4, v22 offset:1584
	ds_write_b32 v4, v23 offset:1848
	ds_write_b32 v4, v24 offset:2112
	ds_write_b32 v4, v25 offset:2376
	ds_write_b32 v4, v26 offset:2640
	ds_write_b32 v4, v27 offset:2904
	ds_write_b32 v4, v28 offset:3168
	ds_write_b32 v4, v29 offset:3432
	ds_write_b32 v4, v30 offset:3696
	ds_write_b32 v4, v31 offset:3960
	ds_write_b32 v4, v32 offset:4224
	ds_write_b32 v4, v33 offset:4488
	ds_write_b32 v4, v34 offset:4752
	ds_write_b32 v4, v35 offset:5016
	ds_write_b32 v4, v36 offset:5280
	ds_write_b32 v4, v37 offset:5544
	ds_write_b32 v4, v38 offset:5808
	ds_write_b32 v4, v39 offset:6072
	ds_write_b32 v4, v40 offset:6336
	ds_write_b32 v4, v41 offset:6600
	ds_write_b32 v4, v42 offset:6864
	ds_write_b32 v4, v43 offset:7128
	ds_write_b32 v4, v44 offset:7392
	ds_write_b32 v4, v45 offset:7656
	ds_write_b32 v4, v46 offset:7920
	ds_write_b32 v4, v47 offset:8184
	s_waitcnt lgkmcnt(0)
	ds_read_b32 v48, v7
	ds_read_b32 v49, v7 offset:132
	ds_read_b32 v50, v7 offset:264
	ds_read_b32 v51, v7 offset:396
	ds_read_b32 v52, v7 offset:528
	ds_read_b32 v53, v7 offset:660
	ds_read_b32 v54, v7 offset:792
	ds_read_b32 v55, v7 offset:924
	ds_read_b32 v56, v7 offset:32
	ds_read_b32 v57, v7 offset:164
	ds_read_b32 v58, v7 offset:296
	ds_read_b32 v59, v7 offset:428
	ds_read_b32 v60, v7 offset:560
	ds_read_b32 v61, v7 offset:692
	ds_read_b32 v62, v7 offset:824
	ds_read_b32 v63, v7 offset:956
	ds_read_b32 v64, v7 offset:64
	ds_read_b32 v65, v7 offset:196
	ds_read_b32 v66, v7 offset:328
	ds_read_b32 v67, v7 offset:460
	ds_read_b32 v68, v7 offset:592
	ds_read_b32 v69, v7 offset:724
	ds_read_b32 v70, v7 offset:856
	ds_read_b32 v71, v7 offset:988
	ds_read_b32 v72, v7 offset:96
	ds_read_b32 v73, v7 offset:228
	ds_read_b32 v74, v7 offset:360
	ds_read_b32 v75, v7 offset:492
	ds_read_b32 v76, v7 offset:624
	ds_read_b32 v77, v7 offset:756
	ds_read_b32 v78, v7 offset:888
	ds_read_b32 v79, v7 offset:1020
	s_waitcnt lgkmcnt(0)
	v_mul_f32_e32 v48, v48, v80
	v_mul_f32_e32 v49, v49, v81
	v_mul_f32_e32 v50, v50, v82
	v_mul_f32_e32 v51, v51, v83
	v_mul_f32_e32 v52, v52, v84
	v_mul_f32_e32 v53, v53, v85
	v_mul_f32_e32 v54, v54, v86
	v_mul_f32_e32 v55, v55, v87
	v_cvt_pk_bf16_f32 v48, v48, v49
	v_cvt_pk_bf16_f32 v49, v50, v51
	v_cvt_pk_bf16_f32 v50, v52, v53
	v_cvt_pk_bf16_f32 v51, v54, v55
	global_store_dwordx4 v10, v[48:51], s[16:17]
	v_mul_f32_e32 v56, v56, v80
	v_mul_f32_e32 v57, v57, v81
	v_mul_f32_e32 v58, v58, v82
	v_mul_f32_e32 v59, v59, v83
	v_mul_f32_e32 v60, v60, v84
	v_mul_f32_e32 v61, v61, v85
	v_mul_f32_e32 v62, v62, v86
	v_mul_f32_e32 v63, v63, v87
	v_cvt_pk_bf16_f32 v56, v56, v57
	v_cvt_pk_bf16_f32 v57, v58, v59
	v_cvt_pk_bf16_f32 v58, v60, v61
	v_cvt_pk_bf16_f32 v59, v62, v63
	global_store_dwordx4 v10, v[56:59], s[16:17] offset:256
	v_mul_f32_e32 v64, v64, v80
	v_mul_f32_e32 v65, v65, v81
	v_mul_f32_e32 v66, v66, v82
	v_mul_f32_e32 v67, v67, v83
	v_mul_f32_e32 v68, v68, v84
	v_mul_f32_e32 v69, v69, v85
	v_mul_f32_e32 v70, v70, v86
	v_mul_f32_e32 v71, v71, v87
	v_cvt_pk_bf16_f32 v64, v64, v65
	v_cvt_pk_bf16_f32 v65, v66, v67
	v_cvt_pk_bf16_f32 v66, v68, v69
	v_cvt_pk_bf16_f32 v67, v70, v71
	global_store_dwordx4 v11, v[64:67], s[16:17] offset:512
	v_mul_f32_e32 v72, v72, v80
	v_mul_f32_e32 v73, v73, v81
	v_mul_f32_e32 v74, v74, v82
	v_mul_f32_e32 v75, v75, v83
	v_mul_f32_e32 v76, v76, v84
	v_mul_f32_e32 v77, v77, v85
	v_mul_f32_e32 v78, v78, v86
	v_mul_f32_e32 v79, v79, v87
	v_cvt_pk_bf16_f32 v72, v72, v73
	v_cvt_pk_bf16_f32 v73, v74, v75
	v_cvt_pk_bf16_f32 v74, v76, v77
	v_cvt_pk_bf16_f32 v75, v78, v79
	global_store_dwordx4 v11, v[72:75], s[16:17] offset:768
	s_add_u32 s9, s9, 0x400
	s_branch .Ltc3d_loop

; #define LAS __attribute__((address_space(3)))
; __device__ __forceinline__ unsigned pk2(float lo, float hi) { f32x2 f = {lo, hi}; bf16x2_t b = __builtin_convertvector(f, bf16x2_t); return __builtin_bit_cast(unsigned, b); }
; __device__ __forceinline__ size_t tiled_off(int row, int col, int nkt) {
;     return ((size_t)(row >> 7) * nkt + (col >> 6)) * 16384 + (size_t)pg8::lds_byte(row & 127, col & 63);
; }
; template <int MAP, bool HASG, bool PERMW>
; __device__ __forceinline__ void tr_store(int K, int N, bf16_t* WT, LAS float* scr, int item, int lane, const float* gk) {
;     const int nblk = N / 32, kb = item / nblk, nb = item % nblk, k0 = 64 * kb, n0 = 32 * nb;
;     asm volatile("s_waitcnt lgkmcnt(0)" ::: "memory");
;     const int c = lane & 7;
;     f32x4 g0 = {1.f, 1.f, 1.f, 1.f}, g1 = {1.f, 1.f, 1.f, 1.f};
;     if (HASG) { g0 = *(const f32x4*)(gk + k0 + 8 * c); g1 = *(const f32x4*)(gk + k0 + 8 * c + 4); }
; #pragma unroll
;     for (int j = 0; j < 4; ++j) { const int n = (lane >> 3) + 8 * j; const LAS float* s = scr + (8 * c) * 33 + n;
;         u32x4 o; o.x = pk2(s[0 * 33] * g0[0], s[1 * 33] * g0[1]); o.y = pk2(s[2 * 33] * g0[2], s[3 * 33] * g0[3]); o.z = pk2(s[4 * 33] * g1[0], s[5 * 33] * g1[1]); o.w = pk2(s[6 * 33] * g1[2], s[7 * 33] * g1[3]);
;         const int wr_ = rowmap<MAP>(n0 + n), slot_ = PERMW ? ((wr_ & ~31) + invperm32(wr_ & 31)) : wr_;
;         *(u32x4*)((char*)WT + tiled_off(slot_, k0 + 8 * c, K / 64)) = o; }
.LBB0_826:
	s_cmpk_lt_u32 s2, 0x80
	s_cbranch_scc1 .Ltc2_done
	v_writelane_b32 v255, s4, 24
	v_writelane_b32 v255, s5, 25
	v_writelane_b32 v255, s6, 26
	v_writelane_b32 v255, s7, 27
	v_writelane_b32 v255, s8, 28
	v_writelane_b32 v255, s9, 29
	v_writelane_b32 v255, s10, 30
	v_writelane_b32 v255, s11, 31
	v_writelane_b32 v255, s12, 32
	v_writelane_b32 v255, s13, 33
	v_writelane_b32 v255, s14, 34
	v_writelane_b32 v255, s15, 35
	v_writelane_b32 v255, s16, 36
	v_writelane_b32 v255, s17, 37
	v_writelane_b32 v255, s18, 38
	v_writelane_b32 v255, s19, 39
	v_writelane_b32 v255, s20, 40
	v_writelane_b32 v255, s21, 41
	v_writelane_b32 v255, s22, 42
	v_writelane_b32 v255, s23, 43
	v_readfirstlane_b32 s8, v234
	s_nop 3
	s_lshr_b32 s8, s8, 6
	s_sub_u32 s18, s2, 0x80
	s_lshl_b32 s18, s18, 3
	s_add_u32 s18, s18, s8
	s_mul_i32 s10, s8, 0x2100
	v_and_b32_e32 v0, 63, v234
	v_and_b32_e32 v1, 31, v0
	v_lshrrev_b32_e32 v2, 5, v0
	v_lshlrev_b32_e32 v3, 13, v2
	v_lshl_add_u32 v3, v1, 2, v3
	v_mul_u32_u24_e32 v4, 33, v2
	v_add_u32_e32 v4, v4, v1
	v_lshl_add_u32 v4, v4, 2, s10
	v_and_b32_e32 v5, 7, v0
	v_lshrrev_b32_e32 v6, 3, v0
	v_mul_u32_u24_e32 v7, 0x108, v5
	v_add_u32_e32 v7, v7, v6
	v_lshl_add_u32 v7, v7, 2, s10
	v_lshrrev_b32_e32 v12, 2, v5
	v_lshlrev_b32_e32 v12, 10, v12
	v_and_b32_e32 v13, 3, v5
	v_lshl_add_u32 v12, v13, 4, v12
	v_lshl_add_u32 v8, v6, 6, v12
	v_xor_b32_e32 v9, 32, v8
	v_add_u32_e32 v9, 0x200, v9
	v_and_b32_e32 v13, 3, v6
	v_lshl_add_u32 v10, v13, 6, v12
	v_bfe_u32 v13, v6, 2, 1
	v_lshl_add_u32 v10, v13, 11, v10
	v_xor_b32_e32 v11, 32, v10
	v_lshlrev_b32_e32 v14, 5, v5
	v_mul_u32_u24_e32 v15, 0x5800, v2
	v_lshl_add_u32 v15, v1, 2, v15
	v_readlane_b32 s4, v254, 10
	v_readlane_b32 s5, v254, 11
	s_nop 3
	s_and_b32 s6, s60, 0x2c00000
	s_add_u32 s4, s4, s6
	s_addc_u32 s5, s5, 0
	s_add_u32 s6, s76, 0xb600000
	s_addc_u32 s7, s77, 0
	s_mov_b32 s9, s18
